# FFT filter-tap load loop: the two conditional mirrored-tap loads issued first and unconditionally (landing v114/v115), so the loop's counted waits are no longer defeated by a full drain
# baseline (speedup 1.0000x reference)
.LBB0_619:
	v_add_u32_e32 v2, s20, v24
	v_ashrrev_i32_e32 v3, 31, v2
	v_lshlrev_b64 v[6:7], 1, v[2:3]
	v_lshl_add_u64 v[8:9], s[2:3], 0, v[6:7]
	v_lshl_add_u64 v[14:15], s[10:11], 0, v[6:7]
	v_lshl_add_u64 v[116:117], v[14:15], 0, s[92:93]
	global_load_ushort v114, v[116:117], off
	global_load_ushort v115, v[14:15], off
	v_add_u32_e32 v6, 0x2200, v2
	v_add_co_u32_e32 v10, vcc, 0x4000, v8
	v_ashrrev_i32_e32 v7, 31, v6
	s_nop 0
	v_addc_co_u32_e32 v11, vcc, 0, v9, vcc
	v_lshlrev_b64 v[6:7], 1, v[6:7]
	global_load_ushort v43, v[10:11], off
	global_load_ushort v48, v[8:9], off
	v_lshl_add_u64 v[10:11], s[2:3], 0, v[6:7]
	v_lshl_add_u64 v[6:7], s[10:11], 0, v[6:7]
	global_load_ushort v38, v[8:9], off offset:1024
	global_load_ushort v42, v[10:11], off
	global_load_ushort v31, v[14:15], off offset:1024
	global_load_ushort v39, v[6:7], off
	global_load_ushort v17, v[8:9], off offset:2048
	v_add_u32_e32 v6, 0x2400, v2
	v_ashrrev_i32_e32 v7, 31, v6
	v_lshlrev_b64 v[6:7], 1, v[6:7]
	v_lshl_add_u64 v[10:11], s[2:3], 0, v[6:7]
	v_lshl_add_u64 v[6:7], s[10:11], 0, v[6:7]
	global_load_ushort v34, v[10:11], off
	global_load_ushort v3, v[14:15], off offset:2048
	global_load_ushort v19, v[6:7], off
	global_load_ushort v0, v[8:9], off offset:3072
	v_add_u32_e32 v6, 0x2600, v2
	v_ashrrev_i32_e32 v7, 31, v6
	v_lshlrev_b64 v[6:7], 1, v[6:7]
	v_lshl_add_u64 v[8:9], s[2:3], 0, v[6:7]
	v_lshl_add_u64 v[6:7], s[10:11], 0, v[6:7]
	global_load_ushort v16, v[8:9], off
	global_load_ushort v18, v[14:15], off offset:3072
	global_load_ushort v22, v[6:7], off
	v_add_u32_e32 v6, 0x800, v2
	v_ashrrev_i32_e32 v7, 31, v6
	v_lshlrev_b64 v[8:9], 1, v[6:7]
	v_lshl_add_u64 v[10:11], s[2:3], 0, v[8:9]
	v_lshl_add_u64 v[8:9], s[10:11], 0, v[8:9]
	global_load_ushort v7, v[10:11], off
	global_load_ushort v25, v[8:9], off
	v_add_u32_e32 v10, 0x2800, v2
	v_ashrrev_i32_e32 v11, 31, v10
	v_lshlrev_b64 v[10:11], 1, v[10:11]
	v_lshl_add_u64 v[12:13], s[2:3], 0, v[10:11]
	v_lshl_add_u64 v[8:9], s[10:11], 0, v[10:11]
	v_add_u32_e32 v10, 0xa00, v2
	v_ashrrev_i32_e32 v11, 31, v10
	global_load_ushort v40, v[12:13], off
	global_load_ushort v32, v[8:9], off
	v_lshlrev_b64 v[8:9], 1, v[10:11]
	v_lshl_add_u64 v[12:13], s[2:3], 0, v[8:9]
	v_lshl_add_u64 v[8:9], s[10:11], 0, v[8:9]
	global_load_ushort v20, v[12:13], off
	global_load_ushort v11, v[8:9], off
	v_add_u32_e32 v12, 0x2a00, v2
	v_ashrrev_i32_e32 v13, 31, v12
	v_lshlrev_b64 v[12:13], 1, v[12:13]
	s_waitcnt vmcnt(20)
	v_lshl_add_u64 v[36:37], s[2:3], 0, v[12:13]
	v_lshl_add_u64 v[8:9], s[10:11], 0, v[12:13]
	global_load_ushort v35, v[36:37], off
	global_load_ushort v23, v[8:9], off
	v_add_u32_e32 v8, 0xc00, v2
	v_ashrrev_i32_e32 v9, 31, v8
	v_lshlrev_b64 v[12:13], 1, v[8:9]
	v_lshl_add_u64 v[36:37], s[2:3], 0, v[12:13]
	v_lshl_add_u64 v[12:13], s[10:11], 0, v[12:13]
	global_load_ushort v9, v[36:37], off
	global_load_ushort v30, v[12:13], off
	v_add_u32_e32 v36, 0x2c00, v2
	v_ashrrev_i32_e32 v37, 31, v36
	v_lshlrev_b64 v[36:37], 1, v[36:37]
	v_lshl_add_u64 v[44:45], s[2:3], 0, v[36:37]
	v_lshl_add_u64 v[12:13], s[10:11], 0, v[36:37]
	global_load_ushort v41, v[44:45], off
	global_load_ushort v33, v[12:13], off
	v_add_u32_e32 v12, 0xe00, v2
	v_ashrrev_i32_e32 v13, 31, v12
	v_lshlrev_b64 v[44:45], 1, v[12:13]
	v_lshl_add_u64 v[36:37], s[2:3], 0, v[44:45]
	v_lshl_add_u64 v[44:45], s[10:11], 0, v[44:45]
	global_load_ushort v21, v[36:37], off
	global_load_ushort v13, v[44:45], off
	v_add_u32_e32 v36, 0x2e00, v2
	v_ashrrev_i32_e32 v37, 31, v36
	v_lshlrev_b64 v[46:47], 1, v[36:37]
	v_lshl_add_u64 v[36:37], s[2:3], 0, v[46:47]
	v_lshl_add_u64 v[44:45], s[10:11], 0, v[46:47]
	global_load_ushort v36, v[36:37], off
	v_ashrrev_i32_e32 v46, 5, v2
	global_load_ushort v37, v[44:45], off
	v_cmp_lt_i32_e32 vcc, 0, v2
	s_waitcnt vmcnt(29)
	v_lshlrev_b32_e32 v45, 16, v43
	v_lshl_add_u32 v43, s20, 3, v90
	s_waitcnt vmcnt(28)
	v_lshlrev_b32_e32 v44, 16, v48
	v_lshl_add_u32 v46, v46, 3, v43
	ds_write_b64 v46, v[44:45]
	v_and_b32_e32 v44, 0x7fffffff, v44
	v_and_b32_e32 v45, 0x7fffffff, v45
	v_pk_add_f32 v[4:5], v[4:5], v[44:45]
	s_and_saveexec_b64 s[82:83], vcc
	s_cbranch_execz .LBB0_621
	v_sub_u32_e32 v15, 0x4000, v2
	v_ashrrev_i32_e32 v45, 5, v15
	v_lshlrev_b32_e32 v15, 3, v15
	v_lshlrev_b32_e32 v45, 3, v45
	v_add3_u32 v45, 0, v15, v45
	v_lshlrev_b32_e32 v15, 16, v114
	v_lshlrev_b32_e32 v14, 16, v115
	ds_write_b64 v45, v[14:15]
	v_and_b32_e32 v15, 0x7fffffff, v15
	v_and_b32_e32 v14, 0x7fffffff, v14
	v_pk_add_f32 v[4:5], v[4:5], v[14:15]
